# prologue token rows: wave sum of squares by DPP adds and lane swaps instead of six LDS permutes
# speedup vs baseline: 1.0056x; 1.0056x over previous
; __device__ __forceinline__ u32x2 pk4(f32x4 v) { u32x2 r; r.x = cvt_pk_bf16(v[0], v[1]); r.y = cvt_pk_bf16(v[2], v[3]); return r; }
; __device__ __forceinline__ float wave_sum(float v) {
; #pragma unroll
;     for (int o = 1; o < 64; o <<= 1) v += __shfl_xor(v, o);
;     return v;
; }
; __device__ __forceinline__ void prologue_phase(const Ctx& C, unsigned char* shm) {
;     ...
;         float s = 0.f;
; #pragma unroll
;         for (int j = 0; j < 4; ++j) { s += v[j][0] * v[j][0] + v[j][1] * v[j][1] + v[j][2] * v[j][2] + v[j][3] * v[j][3];
;             *((u32x2*)(C.XB + (size_t)m * DM) + lane + 64 * j) = pk4(v[j]); }
;         s = wave_sum(s);
;         if (lane == 0) C.RSS[m] = s;
.LBB0_973:
	s_or_b64 exec, exec, s[10:11]
	s_waitcnt vmcnt(3)
	v_mul_f32_e32 v24, v15, v15
	s_waitcnt vmcnt(2)
	v_mul_f32_e32 v25, v11, v11
	v_fmac_f32_e32 v24, v14, v14
	v_fmac_f32_e32 v25, v10, v10
	v_fmac_f32_e32 v24, v16, v16
	v_fmac_f32_e32 v25, v12, v12
	v_fmac_f32_e32 v24, v17, v17
	v_fmac_f32_e32 v25, v13, v13
	v_add_f32_e32 v24, v24, v25
	s_waitcnt vmcnt(1)
	v_mul_f32_e32 v25, v7, v7
	v_fmac_f32_e32 v25, v6, v6
	v_fmac_f32_e32 v25, v8, v8
	v_fmac_f32_e32 v25, v9, v9
	v_add_f32_e32 v24, v25, v24
	s_waitcnt vmcnt(0)
	v_mul_f32_e32 v25, v3, v3
	v_fmac_f32_e32 v25, v2, v2
	v_fmac_f32_e32 v25, v4, v4
	v_fmac_f32_e32 v25, v5, v5
	v_add_f32_e32 v24, v25, v24
	v_cvt_pk_bf16_f32 v14, v14, v15
	v_cvt_pk_bf16_f32 v15, v16, v17
	v_lshl_add_u64 v[16:17], s[62:63], 0, v[22:23]
	v_cvt_pk_bf16_f32 v10, v10, v11
	v_add_co_u32_e32 v16, vcc, 0x6100000, v16
	v_cvt_pk_bf16_f32 v11, v12, v13
	v_cvt_pk_bf16_f32 v6, v6, v7
	v_addc_co_u32_e32 v17, vcc, 0, v17, vcc
	v_cvt_pk_bf16_f32 v7, v8, v9
	v_cvt_pk_bf16_f32 v2, v2, v3
	v_cvt_pk_bf16_f32 v3, v4, v5
	global_store_dwordx2 v[16:17], v[14:15], off
	global_store_dwordx2 v[16:17], v[10:11], off offset:512
	global_store_dwordx2 v[16:17], v[6:7], off offset:1024
	global_store_dwordx2 v[16:17], v[2:3], off offset:1536
	v_add_f32_dpp v24, v24, v24 quad_perm:[1,0,3,2] row_mask:0xf bank_mask:0xf
	s_nop 1
	v_add_f32_dpp v24, v24, v24 quad_perm:[2,3,0,1] row_mask:0xf bank_mask:0xf
	s_nop 1
	v_add_f32_dpp v24, v24, v24 row_half_mirror row_mask:0xf bank_mask:0xf
	s_nop 1
	v_add_f32_dpp v24, v24, v24 row_mirror row_mask:0xf bank_mask:0xf
	s_nop 0
	v_mov_b32_e32 v25, v24
	s_nop 1
	v_permlane16_swap_b32_e32 v24, v25
	v_add_f32_e32 v24, v24, v25
	v_mov_b32_e32 v25, v24
	s_nop 1
	v_permlane32_swap_b32_e32 v24, v25
	v_mov_b32_e32 v6, v24
	v_mov_b32_e32 v7, v25
	s_and_saveexec_b64 s[10:11], s[38:39]
	s_cbranch_execz .LBB0_975
	v_lshl_add_u64 v[2:3], s[62:63], 0, v[18:19]
	s_waitcnt lgkmcnt(0)
	v_add_f32_e32 v4, v6, v7
	global_store_dword v[2:3], v4, off
